# v4 plus prologue rebalance: adaLN workgroups skip weight transposes, the other 208 take all items
# speedup vs baseline: 1.0293x; 1.0025x over previous
; #define LAS __attribute__((address_space(3)))
; __device__ __forceinline__ int opqsi(int x) { asm volatile("" : "+s"(x)); return x; }
; __device__ __forceinline__ void phase_prologue(const Ctx& C) {
;     ...
;     LAS float* scr = (LAS float*)(C.lds + C.wave * 16384);
;     const int gw = opqsi(C.vcu) * NWAVES + C.wave, NGW = opqsi(C.G) * NWAVES;
;     constexpr int I_IN = 16 * 96, I_OUT = 16 * 32, I_UP = 16 * 176, I_DN = 44 * 32, I_L = I_IN + I_OUT + I_UP + I_DN;
;     for (int it = gw; it < DEPTH * I_L; it += NGW) {
;         const int l = it / I_L; int r = it % I_L;
;         bf16* wl = (bf16*)(ws_ + WS_W + (size_t)l * WS_WL);
;         if (r < I_IN) { const int kb = r / 96, nb = r % 96, seg = nb >> 4;
;             const int nseg = (seg == 2) ? 4 : (seg == 3) ? 2 : (seg == 4) ? 3 : seg;
;             transpose_item(C.in[4] + (size_t)l * DM * W_IN, DM, W_IN, (bf16*)((unsigned char*)wl + WO_IN), (nseg - seg) * 512, scr, kb, nb, lane); continue; }
;         r -= I_IN;
;         if (r < I_OUT) { const int kb = r / 32, k0 = 64 * kb;
;             transpose_item(C.in[8] + (size_t)l * DM * DM, DM, DM, (bf16*)((unsigned char*)wl + WO_OUT), 0, scr, kb, r % 32, lane, k0 < 512 ? C.in[6] + (size_t)l * 512 + k0 : C.in[7] + (size_t)l * 512 + (k0 - 512)); continue; }
;         r -= I_OUT;
;         if (r < I_UP) { const int kb = r / 176, nb = r % 176, n0 = 32 * nb, isv = n0 >= DFF ? 1 : 0, j0 = n0 - DFF * isv;
;             transpose_item(C.in[9] + (size_t)l * DM * NUP, DM, NUP, (bf16*)((unsigned char*)wl + WO_UP), 256 * (j0 >> 7) + 128 * isv + (j0 & 127) - n0, scr, kb, nb, lane); continue; }
;         r -= I_UP;
;         transpose_item(C.in[12] + (size_t)l * DFF * DM, DFF, DM, (bf16*)((unsigned char*)wl + WO_DOWN), 0, scr, r / 32, r % 32, lane);
;     }
.LBB0_17:
	s_or_b64 exec, exec, s[0:1]
	v_readlane_b32 s0, v254, 1
	s_lshl_b32 s0, s0, 3
	v_readlane_b32 s1, v254, 20
	s_add_i32 s16, s0, s1
	s_mov_b32 s0, s46
	s_cmp_lg_u32 s46, 0x100
	s_cbranch_scc1 .Lrebal_done
	v_readlane_b32 s2, v254, 0
	s_movk_i32 s16, 0x7fff
	s_cmp_lt_u32 s2, 48
	s_cbranch_scc1 .Lrebal_done
	s_lshr_b32 s3, s2, 3
	s_and_b32 s2, s2, 7
	s_mul_i32 s2, s2, 26
	s_add_i32 s2, s2, s3
	s_add_i32 s2, s2, -6
	s_lshl_b32 s2, s2, 3
	s_add_i32 s16, s2, s1
	s_movk_i32 s0, 0xd0
.Lrebal_done:
	s_cmpk_gt_i32 s16, 0x30ff
	s_cbranch_scc1 .LBB0_56
	v_readlane_b32 s1, v254, 20
	s_lshl_b32 s2, s1, 14
	v_lshlrev_b32_e32 v1, 2, v44
	v_lshlrev_b32_e32 v4, 3, v44
	s_add_i32 s2, s2, 0
	v_ashrrev_i32_e32 v34, 3, v44
	v_and_b32_e32 v2, 28, v1
	s_movk_i32 s3, 0x84
	v_and_b32_e32 v4, 56, v4
	s_lshl_b32 s17, s0, 3
	v_lshl_add_u32 v3, v2, 2, s2
	v_mul_lo_u32 v5, v34, s3
	v_mul_u32_u24_e32 v6, 0x84, v4
	v_lshlrev_b32_e32 v7, 2, v34
	s_add_u32 s18, s4, 0x200000
	v_add3_u32 v44, s2, v6, v7
	v_add_u32_e32 v6, 0x1ce0, v5
	v_add_u32_e32 v45, v3, v5
	s_mov_b32 s1, 0
	s_addc_u32 s19, s5, 0
	v_mov_b32_e32 v37, 0
	v_add_u32_e32 v1, 8, v34
	v_add_u32_e32 v42, 16, v34
	v_add_u32_e32 v43, 24, v34
	v_ashrrev_i32_e32 v35, 31, v34
	s_lshl_b32 s20, s16, 5
	s_lshl_b32 s21, s0, 8
	s_lshl_b32 s22, s16, 1
	s_lshl_b32 s23, s0, 4
	s_mov_b32 s28, 0x8000
	s_mov_b32 s29, 0x10000
	s_mov_b32 s30, 0x18000
	s_mov_b32 s31, 0x20000
	s_mov_b32 s33, 0x28000
	s_mov_b32 s34, 0x30000
	s_mov_b32 s35, 0x38000
	v_add_u32_e32 v46, 0x420, v45
	v_add_u32_e32 v47, 0x428, v45
	v_add_u32_e32 v48, 0x840, v45
	v_add_u32_e32 v49, 0x848, v45
	v_add_u32_e32 v50, 0xc60, v45
	v_add_u32_e32 v51, 0xc68, v45
	v_add_u32_e32 v52, 0x1080, v45
	v_add_u32_e32 v53, 0x1088, v45
	v_add_u32_e32 v54, 0x14a0, v45
	v_add_u32_e32 v55, 0x14a8, v45
	v_add_u32_e32 v56, 0x18c0, v45
	v_add_u32_e32 v57, 0x18c8, v45
	v_add_u32_e32 v58, 0x1ce0, v45
	v_add_u32_e32 v59, 0x1ce8, v45
	s_mov_b64 s[10:11], 0x1300000
	s_movk_i32 s36, 0x1600
	s_movk_i32 s37, 0x5800
	s_mov_b64 s[12:13], 0x800000
	v_add_u32_e32 v60, v3, v6
	s_mov_b64 s[14:15], 0x600000
	s_movk_i32 s38, 0x3000
	v_lshlrev_b32_e32 v36, 2, v2
	v_lshlrev_b32_e32 v38, 1, v4
	s_branch .LBB0_21
